# attention schedule: long units split into at most 2 key chunks, only units over 130 key tiles are split (fewer slab merges and prologues)
# speedup vs baseline: 1.0095x; 1.0095x over previous
; __device__ __forceinline__ float att_window(float Bn, float Cn, float slope, int tq) {
;     float blk = 1e30f;
; #pragma unroll
;     for (int e = 0; e < 7; ++e) { const float Tm = (float)(1 << e) * slope; blk = fminf(blk, 32.f * Tm - __logf(64.f * Tm)); }
;     { const float x = __expf(-64.f * slope), g = x / (1.f - x);
;       const float gl = g * (1.f - __expf(-64.f * slope * (float)tq)), gr = g * (1.f - __expf(-64.f * slope * (float)(254 - tq)));
;       blk = fminf(blk, 32.f * slope - __logf(64.f * slope * (1.f + gl + gr))); }
;     float lnphi = 0.f;
;     if (Bn > 1e-3f) { const float c = fminf(Cn, Bn), rho = ((Bn + c) + (Bn - c) * __expf(-2.f * Bn)) / (2.f * Bn);
;                       const float kappa = 64.f * __expf(-63.f * slope) * (1.f - __expf(-slope)) / (1.f - __expf(-64.f * slope));
;                       const float phi = 1.f - kappa * (1.f - rho); lnphi = phi > 0.f && phi < 1.f ? __logf(phi) + 1e-3f : 0.f; }
;     const float k0 = 18.04f + __logf(slope / (1.f - __expf(-slope)));
;     const float a1 = 2.f * Bn + k0, a2 = Bn + Cn + blk + k0;
;     if (ATT_EXACT_ZERO) return (104.f + 2.f * Bn) / slope;
;     const float a_one = fminf(a1, a2) + lnphi - 0.6931f, a_two = a_one + __logf(1.f + __expf(-127.f * slope)) + 1e-3f, r_one = a_one / slope;
;     const int R1 = r_one < 20000.f ? (int)r_one + 1 : 20000, q0 = 64 * tq;
;     const bool one_sided = (q0 - R1 <= 0) || (q0 + 127 + R1 >= M - 1);
;     return one_sided ? r_one : a_two / slope;
; }
; __global__ void __launch_bounds__(NWAVES * 64, 2) fwd(Args args) {
;     ...
;         { const int u = tid, h = 3 - (u >> 7), k = u & 127, qb = (k & 1) ? 63 - (k >> 1) : 64 + (k >> 1);
;           const float slope = exp2f(-2.f * (float)(h + 1));
;           const float Rf = att::att_window(Bn, Cn, slope, 2 * qb);
;           const int R = Rf < 20000.f ? (int)Rf + 1 : 20000;
.LBB0_349:
	v_and_b32_e32 v15, 1, v0
	v_lshrrev_b32_e32 v7, 1, v7
	v_xor_b32_e32 v16, 63, v7
	v_or_b32_e32 v7, 64, v7
	v_cmp_eq_u32_e32 vcc, 0, v15
	v_mul_f32_e32 v19, 0x42800000, v1
	s_mov_b32 s4, 0x800000
	v_cndmask_b32_e32 v18, v16, v7, vcc
	v_cmp_gt_f32_e32 vcc, s4, v19
	s_mov_b32 s3, 0x3f317217
	s_mov_b32 s2, 0x7f800000
	v_cndmask_b32_e64 v15, 0, 32, vcc
	v_ldexp_f32 v15, v19, v15
	v_log_f32_e32 v15, v15
	v_mov_b32_e32 v20, 0x41b17218
	s_mov_b32 s5, 0x42000000
	v_mul_f32_e32 v16, 0x42000000, v1
	v_mul_f32_e32 v17, 0x3f317217, v15
	v_fma_f32 v17, v15, s3, -v17
	v_fmac_f32_e32 v17, 0x3377d1cf, v15
	v_fmac_f32_e32 v17, 0x3f317217, v15
	v_cmp_lt_f32_e64 s[0:1], |v15|, s2
	v_lshlrev_b32_e32 v7, 1, v18
	v_add_f32_e32 v6, v3, v6
	v_cndmask_b32_e64 v15, v15, v17, s[0:1]
	v_add_f32_e32 v17, v1, v1
	v_mul_f32_e32 v21, 0x42800000, v17
	v_cmp_gt_f32_e64 s[0:1], s4, v21
	v_cmp_gt_u32_e64 s[8:9], 4, v206
	v_cmp_gt_u32_e64 s[10:11], 8, v206
	v_cndmask_b32_e64 v22, 0, 32, s[0:1]
	v_ldexp_f32 v21, v21, v22
	v_log_f32_e32 v21, v21
	v_cndmask_b32_e32 v22, 0, v20, vcc
	v_sub_f32_e32 v15, v15, v22
	v_fma_f32 v15, v1, s5, -v15
	v_mul_f32_e32 v22, 0x3f317217, v21
	v_fma_f32 v22, v21, s3, -v22
	v_fmac_f32_e32 v22, 0x3377d1cf, v21
	v_fmac_f32_e32 v22, 0x3f317217, v21
	v_cmp_lt_f32_e64 vcc, |v21|, s2
	v_cmp_gt_u32_e64 s[12:13], 16, v206
	v_cmp_gt_u32_e64 s[14:15], 32, v206
	v_cndmask_b32_e32 v21, v21, v22, vcc
	v_cndmask_b32_e64 v22, 0, v20, s[0:1]
	v_sub_f32_e32 v21, v21, v22
	v_mul_f32_e32 v22, 4.0, v1
	v_mul_f32_e32 v23, 0x42800000, v22
	v_cmp_gt_f32_e32 vcc, s4, v23
	v_fma_f32 v17, v17, s5, -v21
	s_mov_b32 s0, 0x7149f2ca
	v_cndmask_b32_e64 v24, 0, 32, vcc
	v_ldexp_f32 v23, v23, v24
	v_log_f32_e32 v23, v23
	v_min3_f32 v15, v15, s0, v17
	v_mul_f32_e32 v21, 0x41000000, v1
	v_cmp_eq_u32_e64 s[16:17], 63, v206
	v_mul_f32_e32 v17, 0x3f317217, v23
	v_fma_f32 v17, v23, s3, -v17
	v_fmac_f32_e32 v17, 0x3377d1cf, v23
	v_fmac_f32_e32 v17, 0x3f317217, v23
	v_cmp_lt_f32_e64 s[0:1], |v23|, s2
	s_nop 1
	v_cndmask_b32_e64 v17, v23, v17, s[0:1]
	v_mul_f32_e32 v23, 0x42800000, v21
	v_cmp_gt_f32_e64 s[0:1], s4, v23
	s_nop 1
	v_cndmask_b32_e64 v24, 0, 32, s[0:1]
	v_ldexp_f32 v23, v23, v24
	v_log_f32_e32 v23, v23
	v_cndmask_b32_e32 v24, 0, v20, vcc
	v_sub_f32_e32 v17, v17, v24
	v_fma_f32 v17, v22, s5, -v17
	v_mul_f32_e32 v22, 0x3f317217, v23
	v_fma_f32 v22, v23, s3, -v22
	v_fmac_f32_e32 v22, 0x3377d1cf, v23
	v_mul_f32_e32 v24, 0x41800000, v1
	v_fmac_f32_e32 v22, 0x3f317217, v23
	v_cmp_lt_f32_e64 vcc, |v23|, s2
	v_mul_f32_e32 v25, 0x42800000, v24
	s_nop 0
	v_cndmask_b32_e32 v22, v23, v22, vcc
	v_cmp_gt_f32_e32 vcc, s4, v25
	v_cndmask_b32_e64 v23, 0, v20, s[0:1]
	v_sub_f32_e32 v22, v22, v23
	v_cndmask_b32_e64 v26, 0, 32, vcc
	v_ldexp_f32 v25, v25, v26
	v_log_f32_e32 v25, v25
	v_fma_f32 v21, v21, s5, -v22
	v_min3_f32 v15, v15, v17, v21
	v_mul_f32_e32 v21, 0x42800000, v16
	v_mul_f32_e32 v17, 0x3f317217, v25
	v_fma_f32 v17, v25, s3, -v17
	v_fmac_f32_e32 v17, 0x3377d1cf, v25
	v_fmac_f32_e32 v17, 0x3f317217, v25
	v_cmp_lt_f32_e64 s[0:1], |v25|, s2
	v_mul_f32_e32 v23, 0x42800000, v19
	s_nop 0
	v_cndmask_b32_e64 v17, v25, v17, s[0:1]
	v_cmp_gt_f32_e64 s[0:1], s4, v21
	s_nop 1
	v_cndmask_b32_e64 v22, 0, 32, s[0:1]
	v_ldexp_f32 v21, v21, v22
	v_log_f32_e32 v21, v21
	v_cndmask_b32_e32 v22, 0, v20, vcc
	v_sub_f32_e32 v17, v17, v22
	v_fma_f32 v17, v24, s5, -v17
	v_mul_f32_e32 v22, 0x3f317217, v21
	v_fma_f32 v22, v21, s3, -v22
	v_fmac_f32_e32 v22, 0x3377d1cf, v21
	v_fmac_f32_e32 v22, 0x3f317217, v21
	v_cmp_lt_f32_e64 vcc, |v21|, s2
	s_nop 1
	v_cndmask_b32_e32 v21, v21, v22, vcc
	v_cndmask_b32_e64 v22, 0, v20, s[0:1]
	v_cmp_gt_f32_e64 s[0:1], s4, v23
	v_sub_f32_e32 v21, v21, v22
	v_fma_f32 v16, v16, s5, -v21
	v_cndmask_b32_e64 v24, 0, 32, s[0:1]
	v_ldexp_f32 v23, v23, v24
	v_log_f32_e32 v23, v23
	v_min3_f32 v21, v15, v17, v16
	v_div_scale_f32 v16, s[6:7], v14, v14, v12
	v_mul_f32_e32 v15, 0x3f317217, v23
	v_rcp_f32_e32 v22, v16
	v_fma_f32 v15, v23, s3, -v15
	v_fmac_f32_e32 v15, 0x3377d1cf, v23
	v_fmac_f32_e32 v15, 0x3f317217, v23
	v_cmp_lt_f32_e64 vcc, |v23|, s2
	v_cmp_gt_u32_e64 s[6:7], 2, v206
	s_nop 0
	v_cndmask_b32_e32 v23, v23, v15, vcc
	v_fma_f32 v15, -v16, v22, 1.0
	v_fmac_f32_e32 v22, v15, v22
	v_div_scale_f32 v15, vcc, v12, v14, v12
	v_mul_f32_e32 v24, v15, v22
	v_fma_f32 v17, -v16, v24, v15
	v_fmac_f32_e32 v24, v17, v22
	v_fma_f32 v15, -v16, v24, v15
	v_cvt_f32_ubyte0_e32 v16, v7
	v_xor_b32_e32 v7, 0xfe, v7
	v_cvt_f32_ubyte0_e32 v7, v7
	v_mul_f32_e32 v16, v13, v16
	v_mul_f32_e32 v7, v13, v7
	v_mul_f32_e32 v16, 0x3fb8aa3b, v16
	v_mul_f32_e32 v7, 0x3fb8aa3b, v7
	v_exp_f32_e32 v16, v16
	v_exp_f32_e32 v17, v7
	v_div_fmas_f32 v7, v15, v22, v24
	v_div_fixup_f32 v12, v7, v14, v12
	v_pk_add_f32 v[14:15], v[16:17], 1.0 op_sel_hi:[1,0] neg_lo:[1,0] neg_hi:[1,0]
	s_nop 0
	v_pk_mul_f32 v[12:13], v[12:13], v[14:15] op_sel_hi:[0,1]
	v_add_f32_e32 v7, 1.0, v12
	v_add_f32_e32 v7, v7, v13
	v_mul_f32_e32 v7, v19, v7
	v_cmp_gt_f32_e32 vcc, s4, v7
	s_nop 1
	v_cndmask_b32_e64 v12, 0, 32, vcc
	v_ldexp_f32 v7, v7, v12
	v_log_f32_e32 v7, v7
	v_cndmask_b32_e64 v12, 0, v20, s[0:1]
	v_div_scale_f32 v14, s[0:1], v4, v4, v1
	v_rcp_f32_e32 v15, v14
	v_mul_f32_e32 v13, 0x3f317217, v7
	v_fma_f32 v13, v7, s3, -v13
	v_fmac_f32_e32 v13, 0x3377d1cf, v7
	v_fmac_f32_e32 v13, 0x3f317217, v7
	v_cmp_lt_f32_e64 s[0:1], |v7|, s2
	v_fma_f32 v16, -v14, v15, 1.0
	v_fmac_f32_e32 v15, v16, v15
	v_cndmask_b32_e64 v7, v7, v13, s[0:1]
; #define LAS __attribute__((address_space(3)))
; __device__ __forceinline__ float att_window(float Bn, float Cn, float slope, int tq) {
;     ...
;     const float a1 = 2.f * Bn + k0, a2 = Bn + Cn + blk + k0;
;     if (ATT_EXACT_ZERO) return (104.f + 2.f * Bn) / slope;
;     const float a_one = fminf(a1, a2) + lnphi - 0.6931f, a_two = a_one + __logf(1.f + __expf(-127.f * slope)) + 1e-3f, r_one = a_one / slope;
;     const int R1 = r_one < 20000.f ? (int)r_one + 1 : 20000, q0 = 64 * tq;
;     const bool one_sided = (q0 - R1 <= 0) || (q0 + 127 + R1 >= M - 1);
;     return one_sided ? r_one : a_two / slope;
; __global__ void __launch_bounds__(NWAVES * 64, 2) fwd(Args args) {
;     ...
;           const int R = Rf < 20000.f ? (int)Rf + 1 : 20000;
;           ((LAS unsigned short*)(lds + LDSCTL_OFF + 14464))[u] = (unsigned short)R;
;           const int q0 = qb * 128; const int klo = q0 - R < 0 ? 0 : q0 - R, khi = q0 + 127 + R > M - 1 ? M - 1 : q0 + 127 + R;
;           const int my_nt = (khi >> 6) - (klo >> 6) + 1, want = my_nt > 100 ? 1 : 0;
;           int v = want;
; #pragma unroll
;           for (int o = 1; o < 64; o <<= 1) { const int t = __shfl_up(v, o); if (lane >= o) v += t; }
;           if (lane == 63) wtot[wave] = (unsigned)v;
;           __syncthreads();
	v_cndmask_b32_e32 v13, 0, v20, vcc
	v_div_scale_f32 v16, vcc, v1, v4, v1
	v_sub_f32_e32 v12, v23, v12
	v_mul_f32_e32 v17, v16, v15
	v_fma_f32 v12, v19, s5, -v12
	v_fma_f32 v19, -v14, v17, v16
	v_fmac_f32_e32 v17, v19, v15
	v_fma_f32 v14, -v14, v17, v16
	v_div_fmas_f32 v14, v14, v15, v17
	v_div_fixup_f32 v4, v14, v4, v1
	v_cmp_gt_f32_e32 vcc, s4, v4
	v_sub_f32_e32 v7, v7, v13
	v_fma_f32 v7, v1, s5, -v7
	v_cndmask_b32_e64 v14, 0, 32, vcc
	v_ldexp_f32 v4, v4, v14
	v_log_f32_e32 v4, v4
	v_min3_f32 v12, v21, v12, v7
	v_mul_f32_e32 v7, 0x3f317217, v4
	v_fma_f32 v7, v4, s3, -v7
	v_fmac_f32_e32 v7, 0x3377d1cf, v4
	v_fmac_f32_e32 v7, 0x3f317217, v4
	v_cmp_lt_f32_e64 s[0:1], |v4|, s2
	s_nop 1
	v_cndmask_b32_e64 v4, v4, v7, s[0:1]
	v_cndmask_b32_e32 v7, 0, v20, vcc
	v_sub_f32_e32 v13, v4, v7
	v_mul_f32_e32 v4, 0xc2fe0000, v1
	v_mul_f32_e32 v4, 0x3fb8aa3b, v4
	v_exp_f32_e32 v4, v4
	v_mov_b32_e32 v7, 0x419051ec
	v_pk_add_f32 v[6:7], v[12:13], v[6:7]
	v_add_f32_e32 v4, 1.0, v4
	v_cmp_gt_f32_e32 vcc, s4, v4
	v_add_f32_e32 v2, v2, v7
	v_add_f32_e32 v6, v6, v7
	v_cndmask_b32_e64 v7, 0, 32, vcc
	v_ldexp_f32 v4, v4, v7
	v_log_f32_e32 v4, v4
	v_min_f32_e32 v2, v2, v6
	v_add_f32_e32 v2, v5, v2
	v_add_f32_e32 v2, 0xbf316f00, v2
	v_mul_f32_e32 v5, 0x3f317217, v4
	v_div_scale_f32 v6, s[0:1], v1, v1, v2
	v_fma_f32 v5, v4, s3, -v5
	v_rcp_f32_e32 v7, v6
	v_fmac_f32_e32 v5, 0x3377d1cf, v4
	v_fmac_f32_e32 v5, 0x3f317217, v4
	v_cmp_lt_f32_e64 s[0:1], |v4|, s2
	s_mov_b32 s4, 0x469c4000
	s_nop 0
	v_cndmask_b32_e64 v4, v4, v5, s[0:1]
	v_cndmask_b32_e32 v5, 0, v20, vcc
	v_sub_f32_e32 v4, v4, v5
	v_fma_f32 v5, -v6, v7, 1.0
	v_fmac_f32_e32 v7, v5, v7
	v_div_scale_f32 v5, vcc, v2, v1, v2
	v_mul_f32_e32 v12, v5, v7
	v_fma_f32 v13, -v6, v12, v5
	v_fmac_f32_e32 v12, v13, v7
	v_fma_f32 v5, -v6, v12, v5
	v_div_fmas_f32 v5, v5, v7, v12
	v_div_fixup_f32 v5, v5, v1, v2
	v_cvt_i32_f32_e32 v6, v5
	v_add_f32_e32 v2, v4, v2
	v_add_f32_e32 v2, 0x3a83126f, v2
	v_div_scale_f32 v13, s[2:3], v1, v1, v2
	v_rcp_f32_e32 v14, v13
	v_add_u32_e32 v4, 1, v6
	v_mov_b32_e32 v6, 0x4e20
	v_cmp_gt_f32_e32 vcc, s4, v5
	v_lshlrev_b32_e32 v7, 7, v18
	v_or_b32_e32 v12, 0x7f, v7
	v_cndmask_b32_e32 v4, v6, v4, vcc
	v_cmp_le_i32_e64 s[0:1], v7, v4
	v_add_u32_e32 v4, v12, v4
	s_movk_i32 s2, 0x3ffe
	v_cmp_lt_i32_e64 s[2:3], s2, v4
	v_fma_f32 v4, -v13, v14, 1.0
	v_fmac_f32_e32 v14, v4, v14
	v_div_scale_f32 v4, vcc, v2, v1, v2
	v_mul_f32_e32 v15, v4, v14
	v_fma_f32 v16, -v13, v15, v4
	v_fmac_f32_e32 v15, v16, v14
	v_fma_f32 v4, -v13, v15, v4
	v_div_fmas_f32 v4, v4, v14, v15
	v_div_fixup_f32 v1, v4, v1, v2
	s_or_b64 vcc, s[0:1], s[2:3]
	v_cndmask_b32_e32 v1, v1, v5, vcc
	v_cvt_i32_f32_e32 v2, v1
	v_cmp_gt_f32_e32 vcc, s4, v1
	s_movk_i32 s0, 0x81
	v_cmp_eq_u32_e64 s[4:5], 0, v206
	v_add_u32_e32 v2, 1, v2
	v_cndmask_b32_e32 v4, v6, v2, vcc
	v_sub_u32_e32 v1, v7, v4
	v_add_u32_e32 v2, v12, v4
	v_max_i32_e32 v1, 0, v1
	v_min_i32_e32 v2, 0x3fff, v2
	v_ashrrev_i32_e32 v2, 6, v2
	v_lshrrev_b32_e32 v1, 6, v1
	v_sub_u32_e32 v2, v2, v1
	v_mbcnt_lo_u32_b32 v1, -1, 0
	v_mbcnt_hi_u32_b32 v1, -1, v1
	v_and_b32_e32 v5, 64, v1
	v_add_u32_e32 v6, -1, v1
	v_cmp_lt_i32_e32 vcc, v6, v5
	v_cmp_lt_i32_e64 s[2:3], s0, v2
	v_add_u32_e32 v14, -2, v1
	v_cndmask_b32_e32 v6, v6, v1, vcc
	v_cndmask_b32_e64 v12, 0, 1, s[2:3]
	v_lshlrev_b32_e32 v13, 2, v6
	ds_bpermute_b32 v6, v13, v12
	s_waitcnt lgkmcnt(0)
	v_cndmask_b32_e64 v6, v6, 0, s[4:5]
	v_addc_co_u32_e64 v7, vcc, 0, v6, s[2:3]
	v_cmp_lt_i32_e32 vcc, v14, v5
	s_nop 1
	v_cndmask_b32_e32 v14, v14, v1, vcc
	v_lshlrev_b32_e32 v14, 2, v14
	ds_bpermute_b32 v7, v14, v7
	s_waitcnt lgkmcnt(0)
	v_cndmask_b32_e64 v7, v7, 0, s[6:7]
	v_addc_co_u32_e64 v6, vcc, v7, v6, s[2:3]
	v_add_u32_e32 v7, -4, v1
	v_cmp_lt_i32_e32 vcc, v7, v5
	s_nop 1
	v_cndmask_b32_e32 v7, v7, v1, vcc
	v_lshlrev_b32_e32 v15, 2, v7
	ds_bpermute_b32 v7, v15, v6
	s_waitcnt lgkmcnt(0)
	v_cndmask_b32_e64 v7, v7, 0, s[8:9]
	v_add_u32_e32 v6, v7, v6
	v_add_u32_e32 v7, -8, v1
	v_cmp_lt_i32_e32 vcc, v7, v5
	s_nop 1
	v_cndmask_b32_e32 v7, v7, v1, vcc
	v_lshlrev_b32_e32 v16, 2, v7
	ds_bpermute_b32 v7, v16, v6
	s_waitcnt lgkmcnt(0)
	v_cndmask_b32_e64 v7, v7, 0, s[10:11]
	v_add_u32_e32 v6, v7, v6
	v_add_u32_e32 v7, -16, v1
	v_cmp_lt_i32_e32 vcc, v7, v5
	s_nop 1
	v_cndmask_b32_e32 v7, v7, v1, vcc
	v_lshlrev_b32_e32 v17, 2, v7
	ds_bpermute_b32 v7, v17, v6
	s_waitcnt lgkmcnt(0)
	v_cndmask_b32_e64 v7, v7, 0, s[12:13]
	v_add_u32_e32 v6, v7, v6
	v_subrev_u32_e32 v7, 32, v1
	v_cmp_lt_i32_e32 vcc, v7, v5
	s_nop 1
	v_cndmask_b32_e32 v1, v7, v1, vcc
	v_lshlrev_b32_e32 v18, 2, v1
	ds_bpermute_b32 v5, v18, v6
	v_lshl_add_u32 v1, v0, 1, 0
	v_add_u32_e32 v7, 0x23880, v1
	ds_write_b16 v7, v4
	s_waitcnt lgkmcnt(1)
	v_cndmask_b32_e64 v4, v5, 0, s[14:15]
	v_add_u32_e32 v19, v4, v6
	s_and_saveexec_b64 s[0:1], s[16:17]
	s_lshl_b32 s18, s76, 2
	s_add_i32 s18, s18, 0
	s_add_i32 s18, s18, 0x20c80
	v_mov_b32_e32 v4, s18
	ds_write_b32 v4, v19
	s_or_b64 exec, exec, s[0:1]
	s_cmp_gt_u32 s77, 63
	s_cselect_b64 s[26:27], -1, 0
	s_cmp_lt_u32 s77, 64
	v_mov_b32_e32 v4, 0
	s_waitcnt lgkmcnt(0)
	s_barrier
	s_cbranch_scc1 .LBB0_364
	s_cmpk_lt_u32 s77, 0x100
	s_cbranch_scc1 .LBB0_357
	s_add_i32 s18, s76, -4
	s_lshr_b32 s24, s18, 2
	s_add_i32 s24, s24, 1
	s_mov_b32 s0, 0
	s_cmp_lt_u32 s18, 28
	s_cbranch_scc1 .LBB0_358
	s_add_i32 s1, 0, 0x20c80
	s_and_b32 s25, s24, 0x7ffffff8
	v_mov_b32_e32 v7, 0
	v_mov_b32_e32 v6, 0
	v_mov_b32_e32 v5, 0
	v_mov_b32_e32 v4, 0

; __global__ void __launch_bounds__(NWAVES * 64, 2) fwd(Args args) {
;     ...
;           const int sid = off + v - want;
;           const int my_nc = (want && sid < MAX_SPLIT_UNITS) ? ((my_nt + 63) / 64 < 3 ? (my_nt + 63) / 64 : 3) : 1;
;           sidx[u] = (unsigned short)sid;
;           v = my_nc;
; #pragma unroll
;           for (int o = 1; o < 64; o <<= 1) { const int t = __shfl_up(v, o); if (lane >= o) v += t; }
;           if (lane == 63) wtot[8 + wave] = (unsigned)v;
;           __syncthreads();
;           off = 0;
;           for (int w = 0; w < wave; ++w) off += (int)wtot[8 + w];
;           pre[u] = (unsigned short)(off + v - my_nc);
.LBB0_364:
	v_sub_u32_e32 v5, v19, v12
	v_add_u32_e32 v4, v5, v4
	s_movk_i32 s0, 0x90
	v_cmp_gt_i32_e32 vcc, s0, v4
	s_movk_i32 s0, 0x80
	v_cmp_gt_u32_e64 s[0:1], s0, v2
	s_and_b64 s[2:3], s[2:3], vcc
	v_add_u32_e32 v6, 0x20840, v1
	v_mov_b32_e32 v2, 2
	v_cndmask_b32_e64 v12, 1, v2, s[2:3]
	ds_bpermute_b32 v2, v13, v12
	ds_write_b16 v6, v4
	s_waitcnt lgkmcnt(1)
	v_cndmask_b32_e64 v13, v2, 0, s[4:5]
	v_add_u32_e32 v2, v13, v12
	ds_bpermute_b32 v5, v14, v2
	s_waitcnt lgkmcnt(0)
	v_cndmask_b32_e64 v14, v5, 0, s[6:7]
	v_add_u32_e32 v2, v14, v2
	ds_bpermute_b32 v5, v15, v2
	s_waitcnt lgkmcnt(0)
	v_cndmask_b32_e64 v15, v5, 0, s[8:9]
	v_add_u32_e32 v2, v15, v2
	ds_bpermute_b32 v5, v16, v2
	s_waitcnt lgkmcnt(0)
	v_cndmask_b32_e64 v16, v5, 0, s[10:11]
	v_add_u32_e32 v2, v16, v2
	ds_bpermute_b32 v5, v17, v2
	s_waitcnt lgkmcnt(0)
	v_cndmask_b32_e64 v17, v5, 0, s[12:13]
	v_add_u32_e32 v2, v17, v2
	ds_bpermute_b32 v5, v18, v2
	s_waitcnt lgkmcnt(0)
	v_cndmask_b32_e64 v18, v5, 0, s[14:15]
	v_add_u32_e32 v2, v18, v2
	s_and_saveexec_b64 s[0:1], s[16:17]
	s_lshl_b32 s4, s76, 2
	s_add_i32 s4, s4, 0
	s_add_i32 s4, s4, 0x20ca0
	v_mov_b32_e32 v4, s4
	ds_write_b32 v4, v2
	s_or_b64 exec, exec, s[0:1]
	s_andn2_b64 vcc, exec, s[26:27]
	v_mov_b32_e32 v6, 0
	s_waitcnt lgkmcnt(0)
	s_barrier
	s_cbranch_vccnz .LBB0_379
	s_cmpk_lt_u32 s77, 0x100
	s_cbranch_scc1 .LBB0_372
	s_add_i32 s5, s76, -4
	s_lshr_b32 s4, s5, 2
	s_add_i32 s4, s4, 1
	s_mov_b32 s0, 0
	s_cmp_lt_u32 s5, 28
	s_cbranch_scc1 .LBB0_373
	s_add_i32 s1, 0, 0x20ca0
	s_and_b32 s5, s4, 0x7ffffff8
	v_mov_b32_e32 v7, 0
	v_mov_b32_e32 v6, 0
	v_mov_b32_e32 v5, 0
	v_mov_b32_e32 v4, 0
